# v043 + SSD MFMA section with rolling 4-deep fragment prefetch (counted lgkmcnt) + SSD flush read overlap
# speedup vs baseline: 1.0042x; 1.0035x over previous
.LBB0_568:
	s_cmp_eq_u32 s34, 0
	s_cbranch_scc1 .LBB0_570
	s_andn2_b32 s6, 1, s34
	s_mul_i32 s6, s6, 0xe000
	v_mov_b32_e32 v64, v182
	s_add_i32 s6, s37, s6
	s_waitcnt lgkmcnt(0)
	v_lshrrev_b32_e32 v65, 2, v64
	v_lshl_add_u32 v72, v64, 4, s6
	v_lshlrev_b32_e32 v64, 3, v64
	v_add_u32_e32 v69, s21, v65
	v_and_or_b32 v68, v64, 24, s76
	ds_read_b128 v[64:67], v72 offset:40960
	ds_read_b128 v[248:251], v72 offset:41984
	v_mad_u64_u32 v[68:69], s[6:7], v69, s91, v[68:69]
	v_add_u32_e32 v152, 0xfffdc000, v68
	v_lshl_add_u64 v[70:71], v[152:153], 1, s[26:27]
	v_add_u32_e32 v152, 0xfffee000, v68
	v_lshl_add_u64 v[68:69], v[152:153], 1, s[26:27]
	s_waitcnt lgkmcnt(1)
	global_store_dwordx4 v[70:71], v[64:67], off
	s_waitcnt lgkmcnt(0)
	global_store_dwordx4 v[68:69], v[248:251], off
	s_waitcnt lgkmcnt(0)

.LBB0_572:
	v_mov_b32_e32 v152, v182
	s_nop 0
	v_readlane_b32 s32, v165, 31
	s_nop 3
	v_sub_f32_e32 v248, s32, v165
	v_exp_f32_e32 v249, v165
	v_exp_f32_e32 v248, v248
	v_cmp_gt_u32_e32 vcc, 32, v152
	s_and_saveexec_b64 s[6:7], vcc
	v_lshl_add_u32 v64, v152, 3, s49
	ds_write_b64 v64, v[164:165]
	v_lshl_add_u32 v250, v152, 2, s49
	ds_write_b32 v250, v248 offset:1024
	ds_write_b32 v250, v249 offset:1152
	s_or_b64 exec, exec, s[6:7]
	s_bitcmp1_b32 s34, 0
	s_cselect_b32 s6, 0xe000, 0
	s_add_i32 s42, s6, 0
	v_and_b32_e32 v197, 31, v152
	v_ashrrev_i32_e32 v196, 5, v152
	s_add_i32 s34, s42, s39
	s_waitcnt lgkmcnt(0)
	v_lshlrev_b32_e32 v65, 8, v196
	v_lshlrev_b32_e32 v66, 1, v197
	v_and_b32_e32 v164, 0xffffffe0, v152
	s_waitcnt lgkmcnt(0)
	v_add3_u32 v195, s34, v65, v66
	v_add_u32_e32 v90, s49, v164
	v_mov_b32_e32 v64, s49
	ds_read_b128 v[124:127], v90
	ds_read_b128 v[120:123], v90 offset:16
	ds_read_b32 v198, v64 offset:252
	ds_read_u16 v66, v195 offset:32768
	ds_read_u16 v67, v195 offset:32832
	ds_read_u16 v70, v195 offset:32896
	ds_read_u16 v71, v195 offset:32960
	ds_read_u16 v74, v195 offset:33280
	ds_read_u16 v75, v195 offset:33344
	ds_read_u16 v78, v195 offset:33408
	ds_read_u16 v94, v195 offset:34496
	ds_read_b128 v[132:135], v90 offset:64
	ds_read_b128 v[128:131], v90 offset:80
	ds_read_b128 v[112:115], v90 offset:128
	ds_read_u16 v79, v195 offset:33472
	ds_read_u16 v82, v195 offset:33792
	ds_read_u16 v83, v195 offset:33856
	ds_read_u16 v86, v195 offset:33920
	ds_read_u16 v87, v195 offset:33984
	ds_read_u16 v91, v195 offset:34304
	ds_read_u16 v92, v195 offset:34368
	ds_read_u16 v95, v195 offset:34432
	ds_read_b128 v[116:119], v90 offset:144
	ds_read_b128 v[104:107], v90 offset:192
	ds_read_b128 v[100:103], v90 offset:208
	v_lshrrev_b32_e32 v250, 1, v164
	v_add_u32_e32 v250, s49, v250
	ds_read_b128 v[216:219], v250 offset:1024
	ds_read_b128 v[220:223], v250 offset:1056
	ds_read_b128 v[224:227], v250 offset:1088
	ds_read_b128 v[228:231], v250 offset:1120
	ds_read_b128 v[232:235], v250 offset:1152
	ds_read_b128 v[236:239], v250 offset:1184
	ds_read_b128 v[240:243], v250 offset:1216
	ds_read_b128 v[244:247], v250 offset:1248
	s_waitcnt lgkmcnt(0)
	v_lshlrev_b32_e32 v169, 16, v92
	v_lshlrev_b32_e32 v181, 16, v67
	v_lshlrev_b32_e32 v180, 16, v66
	v_mov_b32_e32 v66, v124
	v_mov_b32_e32 v67, v126
	v_lshlrev_b32_e32 v179, 16, v71
	v_lshlrev_b32_e32 v178, 16, v70
	v_mov_b32_e32 v70, v120
	v_mov_b32_e32 v71, v122
	v_lshlrev_b32_e32 v177, 16, v75
	v_lshlrev_b32_e32 v176, 16, v74
	v_mov_b32_e32 v74, v132
	v_mov_b32_e32 v75, v134
	v_lshlrev_b32_e32 v175, 16, v79
	v_lshlrev_b32_e32 v174, 16, v78
	v_mov_b32_e32 v78, v128
	v_mov_b32_e32 v79, v130
	v_lshlrev_b32_e32 v173, 16, v83
	v_lshlrev_b32_e32 v172, 16, v82
	v_mov_b32_e32 v82, v112
	v_mov_b32_e32 v83, v114
	v_lshlrev_b32_e32 v171, 16, v87
	v_lshlrev_b32_e32 v170, 16, v86
	v_mov_b32_e32 v86, v116
	v_mov_b32_e32 v87, v118
	v_lshlrev_b32_e32 v168, 16, v91
	v_mov_b32_e32 v90, v104
	v_mov_b32_e32 v91, v106
	v_lshlrev_b32_e32 v167, 16, v94
	v_lshlrev_b32_e32 v166, 16, v95
	v_mov_b32_e32 v94, v100
	v_mov_b32_e32 v95, v102
	v_pk_mul_f32 v[66:67], v[66:67], v[180:181]
	v_pk_mul_f32 v[70:71], v[70:71], v[178:179]
	v_pk_mul_f32 v[74:75], v[74:75], v[176:177]
	v_pk_mul_f32 v[78:79], v[78:79], v[174:175]
	v_pk_mul_f32 v[82:83], v[82:83], v[172:173]
	v_pk_mul_f32 v[86:87], v[86:87], v[170:171]
	v_pk_mul_f32 v[90:91], v[90:91], v[168:169]
	v_pk_mul_f32 v[94:95], v[94:95], v[166:167]
	v_pk_mul_f32 v[64:65], v[66:67], v[216:217]
	v_pk_mul_f32 v[68:69], v[70:71], v[218:219]
	v_pk_mul_f32 v[72:73], v[74:75], v[220:221]
	v_pk_mul_f32 v[76:77], v[78:79], v[222:223]
	v_pk_mul_f32 v[80:81], v[82:83], v[224:225]
	v_pk_mul_f32 v[84:85], v[86:87], v[226:227]
	v_pk_mul_f32 v[88:89], v[90:91], v[228:229]
	v_pk_mul_f32 v[92:93], v[94:95], v[230:231]
	v_cvt_pk_bf16_f32 v148, v66, v67
	v_cvt_pk_bf16_f32 v149, v70, v71
	v_cvt_pk_bf16_f32 v150, v74, v75
	v_cvt_pk_bf16_f32 v151, v78, v79
	v_cvt_pk_bf16_f32 v108, v64, v65
	v_cvt_pk_bf16_f32 v109, v68, v69
	v_cvt_pk_bf16_f32 v110, v72, v73
	v_cvt_pk_bf16_f32 v111, v76, v77
	v_cvt_pk_bf16_f32 v140, v82, v83
	v_cvt_pk_bf16_f32 v141, v86, v87
	v_cvt_pk_bf16_f32 v142, v90, v91
	v_cvt_pk_bf16_f32 v143, v94, v95
	v_cvt_pk_bf16_f32 v96, v80, v81
	v_cvt_pk_bf16_f32 v97, v84, v85
	v_cvt_pk_bf16_f32 v98, v88, v89
	v_cvt_pk_bf16_f32 v99, v92, v93
	s_setprio 1
	v_lshlrev_b32_e32 v100, 8, v197
	v_add_u32_e32 v104, 2, v196
	s_waitcnt lgkmcnt(0)
	v_bitop3_b32 v102, v196, v152, 15 bitop3:0x78
	v_lshlrev_b32_e32 v102, 4, v102
	v_add3_u32 v102, v102, v100, s42
	ds_read_b128 v[216:219], v102 offset:8192
	ds_read_b128 v[220:223], v102
	v_add_u32_e32 v102, 2, v196
	v_bitop3_b32 v102, v102, v152, 15 bitop3:0x78
	v_lshlrev_b32_e32 v102, 4, v102
	v_add3_u32 v102, v102, v100, s42
	ds_read_b128 v[224:227], v102 offset:8192
	ds_read_b128 v[228:231], v102
	v_add_u32_e32 v102, 4, v196
	v_bitop3_b32 v102, v102, v152, 15 bitop3:0x78
	v_lshlrev_b32_e32 v102, 4, v102
	v_add3_u32 v102, v102, v100, s42
	ds_read_b128 v[136:139], v102 offset:8192
	ds_read_b128 v[144:147], v102
	v_add_u32_e32 v102, 6, v196
	v_bitop3_b32 v102, v102, v152, 15 bitop3:0x78
	v_lshlrev_b32_e32 v102, 4, v102
	v_add3_u32 v102, v102, v100, s42
	ds_read_b128 v[200:203], v102 offset:8192
	ds_read_b128 v[204:207], v102
	v_cvt_pk_bf16_f32 v208, v0, v1
	v_cvt_pk_bf16_f32 v209, v2, v3
	v_cvt_pk_bf16_f32 v210, v4, v5
	v_cvt_pk_bf16_f32 v211, v6, v7
	s_waitcnt lgkmcnt(6)
	v_mfma_f32_32x32x16_bf16 v[80:95], v[220:223], v[216:219], 0
	v_cvt_pk_bf16_f32 v212, v8, v9
	v_cvt_pk_bf16_f32 v213, v10, v11
	v_cvt_pk_bf16_f32 v214, v12, v13
	v_cvt_pk_bf16_f32 v215, v14, v15
	v_mfma_f32_32x32x16_bf16 v[64:79], v[216:219], v[208:211], 0
	v_add_u32_e32 v102, 8, v196
	v_bitop3_b32 v102, v102, v152, 15 bitop3:0x78
	v_lshlrev_b32_e32 v102, 4, v102
	v_add3_u32 v102, v102, v100, s42
	ds_read_b128 v[216:219], v102 offset:8192
	ds_read_b128 v[220:223], v102
	s_waitcnt lgkmcnt(6)
	v_mfma_f32_32x32x16_bf16 v[80:95], v[228:231], v[224:227], v[80:95]
	v_cvt_pk_bf16_f32 v208, v16, v17
	v_cvt_pk_bf16_f32 v209, v18, v19
	v_cvt_pk_bf16_f32 v210, v20, v21
	v_cvt_pk_bf16_f32 v211, v22, v23
	v_mfma_f32_32x32x16_bf16 v[64:79], v[224:227], v[212:215], v[64:79]
	v_add_u32_e32 v102, 10, v196
	v_bitop3_b32 v102, v102, v152, 15 bitop3:0x78
	v_lshlrev_b32_e32 v102, 4, v102
	v_add3_u32 v102, v102, v100, s42
	ds_read_b128 v[224:227], v102 offset:8192
	ds_read_b128 v[228:231], v102
	s_waitcnt lgkmcnt(6)
	v_mfma_f32_32x32x16_bf16 v[80:95], v[144:147], v[136:139], v[80:95]
	v_cvt_pk_bf16_f32 v212, v24, v25
	v_cvt_pk_bf16_f32 v213, v26, v27
	v_cvt_pk_bf16_f32 v214, v28, v29
	v_cvt_pk_bf16_f32 v215, v30, v31
	v_mfma_f32_32x32x16_bf16 v[64:79], v[136:139], v[208:211], v[64:79]
	v_add_u32_e32 v102, 12, v196
	v_bitop3_b32 v102, v102, v152, 15 bitop3:0x78
	v_lshlrev_b32_e32 v102, 4, v102
	v_add3_u32 v102, v102, v100, s42
	ds_read_b128 v[136:139], v102 offset:8192
	ds_read_b128 v[144:147], v102
	s_waitcnt lgkmcnt(6)
	v_mfma_f32_32x32x16_bf16 v[80:95], v[204:207], v[200:203], v[80:95]
	v_cvt_pk_bf16_f32 v208, v32, v33
	v_cvt_pk_bf16_f32 v209, v34, v35
	v_cvt_pk_bf16_f32 v210, v36, v37
	v_cvt_pk_bf16_f32 v211, v38, v39
	v_mfma_f32_32x32x16_bf16 v[64:79], v[200:203], v[212:215], v[64:79]
	v_add_u32_e32 v102, 14, v196
	v_bitop3_b32 v102, v102, v152, 15 bitop3:0x78
	v_lshlrev_b32_e32 v102, 4, v102
	v_add3_u32 v102, v102, v100, s42
	ds_read_b128 v[200:203], v102 offset:8192
	ds_read_b128 v[204:207], v102
	s_waitcnt lgkmcnt(6)
	v_mfma_f32_32x32x16_bf16 v[80:95], v[220:223], v[216:219], v[80:95]
	v_cvt_pk_bf16_f32 v212, v40, v41
	v_cvt_pk_bf16_f32 v213, v42, v43
	v_mfma_f32_32x32x16_bf16 v[64:79], v[216:219], v[208:211], v[64:79]
	v_cvt_pk_bf16_f32 v214, v44, v45
	v_cvt_pk_bf16_f32 v215, v46, v47
	s_waitcnt lgkmcnt(4)
	v_mfma_f32_32x32x16_bf16 v[80:95], v[228:231], v[224:227], v[80:95]
	v_cvt_pk_bf16_f32 v208, v48, v49
	v_cvt_pk_bf16_f32 v209, v50, v51
	v_mfma_f32_32x32x16_bf16 v[64:79], v[224:227], v[212:215], v[64:79]
	v_cvt_pk_bf16_f32 v210, v52, v53
	v_cvt_pk_bf16_f32 v211, v54, v55
	s_waitcnt lgkmcnt(2)
	v_mfma_f32_32x32x16_bf16 v[80:95], v[144:147], v[136:139], v[80:95]
	v_cvt_pk_bf16_f32 v212, v56, v57
	v_cvt_pk_bf16_f32 v213, v58, v59
	v_mfma_f32_32x32x16_bf16 v[64:79], v[136:139], v[208:211], v[64:79]
	v_cvt_pk_bf16_f32 v214, v60, v61
	v_cvt_pk_bf16_f32 v215, v62, v63
	s_waitcnt lgkmcnt(0)
	v_mfma_f32_32x32x16_bf16 v[80:95], v[204:207], v[200:203], v[80:95]
	s_nop 0
	v_mfma_f32_32x32x16_bf16 v[64:79], v[200:203], v[212:215], v[64:79]
	s_setprio 0
	v_sub_f32_e32 v216, v165, v125
	v_sub_f32_e32 v217, v165, v127
	v_sub_f32_e32 v218, v165, v121
	v_sub_f32_e32 v219, v165, v123
	v_sub_f32_e32 v220, v165, v133
	v_sub_f32_e32 v221, v165, v135
	v_sub_f32_e32 v222, v165, v129
	v_sub_f32_e32 v223, v165, v131
	v_sub_f32_e32 v224, v165, v113
	v_sub_f32_e32 v225, v165, v115
	v_sub_f32_e32 v226, v165, v117
	v_sub_f32_e32 v227, v165, v119
	v_sub_f32_e32 v228, v165, v105
	v_sub_f32_e32 v229, v165, v107
	v_sub_f32_e32 v230, v165, v101
	v_sub_f32_e32 v231, v165, v103
	v_exp_f32_e32 v216, v216
	v_exp_f32_e32 v217, v217
	v_exp_f32_e32 v218, v218
	v_exp_f32_e32 v219, v219
	v_exp_f32_e32 v220, v220
	v_exp_f32_e32 v221, v221
	v_exp_f32_e32 v222, v222
	v_exp_f32_e32 v223, v223
	v_exp_f32_e32 v224, v224
	v_exp_f32_e32 v225, v225
	v_exp_f32_e32 v226, v226
	v_exp_f32_e32 v227, v227
	v_exp_f32_e32 v228, v228
	v_exp_f32_e32 v229, v229
	v_exp_f32_e32 v230, v230
	v_exp_f32_e32 v231, v231
	v_mul_f32_e32 v216, v216, v80
	v_mul_f32_e32 v217, v217, v81
	v_mul_f32_e32 v218, v218, v82
	v_mul_f32_e32 v219, v219, v83
	v_mul_f32_e32 v220, v220, v84
	v_mul_f32_e32 v221, v221, v85
	v_mul_f32_e32 v222, v222, v86
	v_mul_f32_e32 v223, v223, v87
	v_mul_f32_e32 v224, v224, v88
	v_mul_f32_e32 v225, v225, v89
	v_mul_f32_e32 v226, v226, v90
	v_mul_f32_e32 v227, v227, v91
	v_mul_f32_e32 v228, v228, v92
	v_mul_f32_e32 v229, v229, v93
	v_mul_f32_e32 v230, v230, v94
	v_mul_f32_e32 v231, v231, v95
	s_mov_b32 s6, 0xffffffff
	s_mov_b32 s7, 0xfffffff0
	v_cndmask_b32_e64 v216, 0, v216, s[6:7]
	s_mov_b32 s6, 0xfffffffe
	s_mov_b32 s7, 0xffffffe0
	v_cndmask_b32_e64 v217, 0, v217, s[6:7]
	s_mov_b32 s6, 0xfffffffc
	s_mov_b32 s7, 0xffffffc0
	v_cndmask_b32_e64 v218, 0, v218, s[6:7]
	s_mov_b32 s6, 0xfffffff8
	s_mov_b32 s7, 0xffffff80
	v_cndmask_b32_e64 v219, 0, v219, s[6:7]
	s_mov_b32 s6, 0xffffff00
	s_mov_b32 s7, 0xfffff000
	v_cndmask_b32_e64 v220, 0, v220, s[6:7]
	s_mov_b32 s6, 0xfffffe00
	s_mov_b32 s7, 0xffffe000
	v_cndmask_b32_e64 v221, 0, v221, s[6:7]
	s_mov_b32 s6, 0xfffffc00
	s_mov_b32 s7, 0xffffc000
	v_cndmask_b32_e64 v222, 0, v222, s[6:7]
	s_mov_b32 s6, 0xfffff800
	s_mov_b32 s7, 0xffff8000
	v_cndmask_b32_e64 v223, 0, v223, s[6:7]
	s_mov_b32 s6, 0xffff0000
	s_mov_b32 s7, 0xfff00000
	v_cndmask_b32_e64 v224, 0, v224, s[6:7]
	s_mov_b32 s6, 0xfffe0000
	s_mov_b32 s7, 0xffe00000
	v_cndmask_b32_e64 v225, 0, v225, s[6:7]
	s_mov_b32 s6, 0xfffc0000
	s_mov_b32 s7, 0xffc00000
	v_cndmask_b32_e64 v226, 0, v226, s[6:7]
	s_mov_b32 s6, 0xfff80000
	s_mov_b32 s7, 0xff800000
	v_cndmask_b32_e64 v227, 0, v227, s[6:7]
	s_mov_b32 s6, 0xff000000
	s_mov_b32 s7, 0xf0000000
	v_cndmask_b32_e64 v228, 0, v228, s[6:7]
	s_mov_b32 s6, 0xfe000000
	s_mov_b32 s7, 0xe0000000
	v_cndmask_b32_e64 v229, 0, v229, s[6:7]
	s_mov_b32 s6, 0xfc000000
	s_mov_b32 s7, 0xc0000000
	v_cndmask_b32_e64 v230, 0, v230, s[6:7]
	s_mov_b32 s6, 0xf8000000
	s_mov_b32 s7, 0x80000000
	v_cndmask_b32_e64 v231, 0, v231, s[6:7]
	v_cvt_pk_bf16_f32 v80, v216, v217
	v_cvt_pk_bf16_f32 v81, v218, v219
	v_cvt_pk_bf16_f32 v82, v220, v221
	v_cvt_pk_bf16_f32 v83, v222, v223
	v_lshrrev_b32_e32 v112, 2, v152
	v_bitop3_b32 v114, v112, v196, 3 bitop3:0x6c
	v_mfma_f32_32x32x16_bf16 v[80:95], v[80:83], v[148:151], 0
	v_cvt_pk_bf16_f32 v148, v224, v225
	v_cvt_pk_bf16_f32 v149, v226, v227
	v_cvt_pk_bf16_f32 v150, v228, v229
	v_cvt_pk_bf16_f32 v151, v230, v231
	v_bitop3_b32 v104, v104, v112, 3 bitop3:0x78
	v_lshlrev_b32_e32 v102, 6, v197
	v_add_u32_e32 v106, s42, v102
	v_lshl_add_u32 v114, v114, 4, v106
	v_mfma_f32_32x32x16_bf16 v[80:95], v[148:151], v[140:143], v[80:95]
	ds_read_b128 v[140:143], v114 offset:16384
	ds_read_b128 v[148:151], v114 offset:18432
	v_exp_f32_e32 v100, v198
	v_lshl_add_u32 v104, v104, 4, v106
	v_pk_mul_f32 v[14:15], v[14:15], v[100:101] op_sel_hi:[1,0]
	v_pk_mul_f32 v[12:13], v[12:13], v[100:101] op_sel_hi:[1,0]
	v_pk_mul_f32 v[10:11], v[10:11], v[100:101] op_sel_hi:[1,0]
	v_pk_mul_f32 v[8:9], v[8:9], v[100:101] op_sel_hi:[1,0]
	v_pk_mul_f32 v[6:7], v[6:7], v[100:101] op_sel_hi:[1,0]
	v_pk_mul_f32 v[4:5], v[4:5], v[100:101] op_sel_hi:[1,0]
	v_pk_mul_f32 v[2:3], v[2:3], v[100:101] op_sel_hi:[1,0]
	v_pk_mul_f32 v[0:1], v[0:1], v[100:101] op_sel_hi:[1,0]
	v_pk_mul_f32 v[30:31], v[30:31], v[100:101] op_sel_hi:[1,0]
	v_pk_mul_f32 v[28:29], v[28:29], v[100:101] op_sel_hi:[1,0]
	s_waitcnt lgkmcnt(0)
	v_mfma_f32_32x32x16_bf16 v[0:15], v[140:143], v[108:111], v[0:15]
	ds_read_b128 v[140:143], v104 offset:16384
	ds_read_b128 v[196:199], v104 offset:18432
	v_mul_f32_e64 v26, v26, v100
	v_mul_f32_e64 v27, v27, v100
	v_mul_f32_e64 v24, v24, v100
	v_mul_f32_e64 v25, v25, v100
	v_pk_mul_f32 v[22:23], v[22:23], v[100:101] op_sel_hi:[1,0]
	v_pk_mul_f32 v[20:21], v[20:21], v[100:101] op_sel_hi:[1,0]
	v_pk_mul_f32 v[18:19], v[18:19], v[100:101] op_sel_hi:[1,0]
	v_pk_mul_f32 v[16:17], v[16:17], v[100:101] op_sel_hi:[1,0]
	s_waitcnt lgkmcnt(0)
	v_mfma_f32_32x32x16_bf16 v[0:15], v[140:143], v[96:99], v[0:15]
	ds_read_b128 v[140:143], v114 offset:20480
	v_mul_f32_e64 v46, v46, v100
	v_mul_f32_e64 v47, v47, v100
	v_mul_f32_e64 v44, v44, v100
	v_mul_f32_e64 v45, v45, v100
	v_pk_mul_f32 v[42:43], v[42:43], v[100:101] op_sel_hi:[1,0]
	v_pk_mul_f32 v[40:41], v[40:41], v[100:101] op_sel_hi:[1,0]
	v_pk_mul_f32 v[38:39], v[38:39], v[100:101] op_sel_hi:[1,0]
	v_pk_mul_f32 v[36:37], v[36:37], v[100:101] op_sel_hi:[1,0]
	v_mfma_f32_32x32x16_bf16 v[16:31], v[148:151], v[108:111], v[16:31]
	v_mul_f32_e64 v34, v34, v100
	v_mul_f32_e64 v35, v35, v100
	v_mul_f32_e64 v32, v32, v100
	v_mul_f32_e64 v33, v33, v100
	ds_read_b128 v[148:151], v114 offset:22528
	v_fma_f32 v64, v232, v64, v80
	v_fmac_f32_e32 v64, v159, v180
	v_pk_mul_f32 v[62:63], v[62:63], v[100:101] op_sel_hi:[1,0]
	v_pk_mul_f32 v[60:61], v[60:61], v[100:101] op_sel_hi:[1,0]
	v_mfma_f32_32x32x16_bf16 v[16:31], v[196:199], v[96:99], v[16:31]
	v_mul_f32_e64 v58, v58, v100
	v_mul_f32_e64 v59, v59, v100
	v_mul_f32_e64 v56, v56, v100
	v_mul_f32_e64 v57, v57, v100
	v_mul_f32_e64 v54, v54, v100
	v_mul_f32_e64 v55, v55, v100
	v_pk_mul_f32 v[52:53], v[52:53], v[100:101] op_sel_hi:[1,0]
	v_pk_mul_f32 v[50:51], v[50:51], v[100:101] op_sel_hi:[1,0]
	v_pk_mul_f32 v[48:49], v[48:49], v[100:101] op_sel_hi:[1,0]
	s_waitcnt lgkmcnt(0)
	v_mfma_f32_32x32x16_bf16 v[32:47], v[140:143], v[108:111], v[32:47]
	ds_read_b128 v[196:199], v104 offset:20480
	ds_read_b128 v[140:143], v104 offset:22528
	ds_read_u16 v104, v195 offset:40960
	ds_read_u16 v106, v195 offset:41024
	ds_read_u16 v112, v195 offset:41088
	ds_read_u16 v114, v195 offset:41152
	ds_read_u16 v116, v195 offset:41472
	ds_read_u16 v118, v195 offset:41536
	ds_read_u16 v120, v195 offset:41600
	ds_read_u16 v122, v195 offset:41664
	s_waitcnt lgkmcnt(0)
	v_lshlrev_b32_e32 v104, 16, v104
	v_mul_f32_e32 v124, 0xbfb8aa3b, v104
	v_exp_f32_e32 v124, v124
	s_nop 0
	v_add_f32_e32 v124, 1.0, v124
	v_rcp_f32_e32 v124, v124
	v_mfma_f32_32x32x16_bf16 v[48:63], v[148:151], v[108:111], v[48:63]
	v_mul_f32_e32 v80, v124, v104
	v_lshlrev_b32_e32 v104, 16, v106
	v_mul_f32_e32 v106, 0xbfb8aa3b, v104
	v_exp_f32_e32 v106, v106
	v_mul_f32_e32 v64, v64, v80
	v_cvt_pk_bf16_f32 v64, v64, s0
	v_add_f32_e32 v106, 1.0, v106
	ds_write_b16 v195, v64 offset:40960
	v_fma_f32 v64, v233, v65, v81
	v_lshlrev_b32_e32 v80, 16, v112
	v_rcp_f32_e32 v106, v106
	v_mul_f32_e32 v81, 0xbfb8aa3b, v80
	v_exp_f32_e32 v81, v81
	v_fmac_f32_e32 v64, v159, v181
	v_mul_f32_e32 v65, v106, v104
	v_mul_f32_e32 v64, v64, v65
	v_add_f32_e32 v81, 1.0, v81
	v_rcp_f32_e32 v81, v81
	v_cvt_pk_bf16_f32 v64, v64, s0
	ds_write_b16 v195, v64 offset:41024
	v_fma_f32 v64, v234, v66, v82
	v_lshlrev_b32_e32 v66, 16, v114
	v_mul_f32_e32 v65, v81, v80
	v_mul_f32_e32 v80, 0xbfb8aa3b, v66
	v_exp_f32_e32 v80, v80
	v_fmac_f32_e32 v64, v159, v178
	v_mul_f32_e32 v64, v64, v65
	v_add_f32_e32 v80, 1.0, v80
	v_rcp_f32_e32 v80, v80
	v_cvt_pk_bf16_f32 v64, v64, s0
	ds_write_b16 v195, v64 offset:41088
	v_fma_f32 v64, v235, v67, v83
	v_mul_f32_e32 v65, v80, v66
	v_lshlrev_b32_e32 v66, 16, v116
	v_mul_f32_e32 v67, 0xbfb8aa3b, v66
	v_exp_f32_e32 v67, v67
	v_fmac_f32_e32 v64, v159, v179
	v_mul_f32_e32 v64, v64, v65
	v_add_f32_e32 v67, 1.0, v67
	v_rcp_f32_e32 v67, v67
	v_cvt_pk_bf16_f32 v64, v64, s0
	ds_write_b16 v195, v64 offset:41152
	v_fma_f32 v64, v236, v68, v84
	v_mul_f32_e32 v65, v67, v66
	v_lshlrev_b32_e32 v66, 16, v118
	v_mul_f32_e32 v67, 0xbfb8aa3b, v66
	v_exp_f32_e32 v67, v67
	v_fmac_f32_e32 v64, v159, v176
	v_mul_f32_e32 v64, v64, v65
	v_add_f32_e32 v67, 1.0, v67
	v_rcp_f32_e32 v67, v67
	v_cvt_pk_bf16_f32 v64, v64, s0
	ds_write_b16 v195, v64 offset:41472
	v_fma_f32 v64, v237, v69, v85
	v_mul_f32_e32 v65, v67, v66
	v_lshlrev_b32_e32 v66, 16, v120
	v_mul_f32_e32 v67, 0xbfb8aa3b, v66
	v_exp_f32_e32 v67, v67
	v_fmac_f32_e32 v64, v159, v177
	v_mul_f32_e32 v64, v64, v65
	v_add_f32_e32 v67, 1.0, v67
	v_rcp_f32_e32 v67, v67
	v_cvt_pk_bf16_f32 v64, v64, s0
	ds_write_b16 v195, v64 offset:41536
	v_fma_f32 v64, v238, v70, v86
	v_mul_f32_e32 v65, v67, v66
	v_lshlrev_b32_e32 v66, 16, v122
	v_mul_f32_e32 v67, 0xbfb8aa3b, v66
	v_exp_f32_e32 v67, v67
	v_fmac_f32_e32 v64, v159, v174
	v_mul_f32_e32 v64, v64, v65
	v_add_f32_e32 v67, 1.0, v67
	v_rcp_f32_e32 v67, v67
	v_cvt_pk_bf16_f32 v64, v64, s0
	ds_write_b16 v195, v64 offset:41600
	v_fma_f32 v64, v239, v71, v87
	v_mul_f32_e32 v65, v67, v66
	ds_read_u16 v66, v195 offset:41984
	ds_read_u16 v67, v195 offset:42048
	ds_read_u16 v68, v195 offset:42112
	ds_read_u16 v69, v195 offset:42176
	ds_read_u16 v70, v195 offset:42496
	ds_read_u16 v71, v195 offset:42560
	ds_read_u16 v80, v195 offset:42624
	ds_read_u16 v81, v195 offset:42688
	s_waitcnt lgkmcnt(0)
	v_lshlrev_b32_e32 v66, 16, v66
	v_mul_f32_e32 v82, 0xbfb8aa3b, v66
	v_exp_f32_e32 v82, v82
	v_fmac_f32_e32 v64, v159, v175
	v_mul_f32_e32 v64, v64, v65
	v_add_f32_e32 v82, 1.0, v82
	v_rcp_f32_e32 v82, v82
	v_cvt_pk_bf16_f32 v64, v64, s0
	ds_write_b16 v195, v64 offset:41664
	v_fma_f32 v64, v240, v72, v88
	v_mul_f32_e32 v65, v82, v66
	v_lshlrev_b32_e32 v66, 16, v67
	v_mul_f32_e32 v67, 0xbfb8aa3b, v66
	v_exp_f32_e32 v67, v67
	v_fmac_f32_e32 v64, v159, v172
	v_mul_f32_e32 v64, v64, v65
	v_add_f32_e32 v67, 1.0, v67
	v_rcp_f32_e32 v67, v67
	v_cvt_pk_bf16_f32 v64, v64, s0
	ds_write_b16 v195, v64 offset:41984
	v_fma_f32 v64, v241, v73, v89
	v_mul_f32_e32 v65, v67, v66
	v_lshlrev_b32_e32 v66, 16, v68
	v_mul_f32_e32 v67, 0xbfb8aa3b, v66
	v_exp_f32_e32 v67, v67
	v_fmac_f32_e32 v64, v159, v173
	v_mul_f32_e32 v64, v64, v65
	v_add_f32_e32 v67, 1.0, v67
	v_rcp_f32_e32 v67, v67
	v_cvt_pk_bf16_f32 v64, v64, s0
	ds_write_b16 v195, v64 offset:42048
	v_fma_f32 v64, v242, v74, v90
	v_mul_f32_e32 v65, v67, v66
	v_lshlrev_b32_e32 v66, 16, v69
	v_mul_f32_e32 v67, 0xbfb8aa3b, v66
	v_exp_f32_e32 v67, v67
	v_fmac_f32_e32 v64, v159, v170
	v_mul_f32_e32 v64, v64, v65
	v_add_f32_e32 v67, 1.0, v67
	v_rcp_f32_e32 v67, v67
	v_cvt_pk_bf16_f32 v64, v64, s0
	ds_write_b16 v195, v64 offset:42112
	v_fma_f32 v64, v243, v75, v91
	v_mul_f32_e32 v65, v67, v66
	v_lshlrev_b32_e32 v66, 16, v70
	v_mul_f32_e32 v67, 0xbfb8aa3b, v66
	v_exp_f32_e32 v67, v67
	v_fmac_f32_e32 v64, v159, v171
	v_mul_f32_e32 v64, v64, v65
	v_add_f32_e32 v67, 1.0, v67
	v_rcp_f32_e32 v67, v67
	v_cvt_pk_bf16_f32 v64, v64, s0
	ds_write_b16 v195, v64 offset:42176
	v_fma_f32 v64, v244, v76, v92
	v_mul_f32_e32 v65, v67, v66
	v_lshlrev_b32_e32 v66, 16, v71
	v_mul_f32_e32 v67, 0xbfb8aa3b, v66
	v_exp_f32_e32 v67, v67
	v_fmac_f32_e32 v64, v159, v168
	v_mul_f32_e32 v64, v64, v65
	v_add_f32_e32 v67, 1.0, v67
	v_rcp_f32_e32 v67, v67
	v_cvt_pk_bf16_f32 v64, v64, s0
	ds_write_b16 v195, v64 offset:42496
	v_fma_f32 v64, v245, v77, v93
	v_mul_f32_e32 v65, v67, v66
	v_lshlrev_b32_e32 v66, 16, v80
	v_mul_f32_e32 v67, 0xbfb8aa3b, v66
	v_exp_f32_e32 v67, v67
	v_fmac_f32_e32 v64, v159, v169
	v_mul_f32_e32 v64, v64, v65
	v_add_f32_e32 v67, 1.0, v67
	v_rcp_f32_e32 v67, v67
	v_cvt_pk_bf16_f32 v64, v64, s0
	ds_write_b16 v195, v64 offset:42560
	v_fma_f32 v64, v246, v78, v94
	v_mul_f32_e32 v65, v67, v66
	v_lshlrev_b32_e32 v66, 16, v81
	v_mul_f32_e32 v67, 0xbfb8aa3b, v66
	v_exp_f32_e32 v67, v67
	v_fmac_f32_e32 v64, v159, v166
	v_mul_f32_e32 v64, v64, v65
	v_add_f32_e32 v67, 1.0, v67
	v_rcp_f32_e32 v67, v67
	v_cvt_pk_bf16_f32 v64, v64, s0
	v_fmac_f32_e32 v95, v247, v79
	ds_write_b16 v195, v64 offset:42624
	v_fmac_f32_e32 v95, v159, v167
	v_mul_f32_e32 v64, v67, v66
	v_mul_f32_e32 v64, v95, v64
	v_cvt_pk_bf16_f32 v64, v64, s0
	ds_write_b16 v195, v64 offset:42688
	s_waitcnt lgkmcnt(0)
	v_add3_u32 v68, s34, v102, v164
	ds_read_b128 v[64:67], v68 offset:40960
	ds_read_b128 v[68:71], v68 offset:40976
	v_mfma_f32_32x32x16_bf16 v[32:47], v[196:199], v[96:99], v[32:47]
	s_waitcnt lgkmcnt(0)
	v_lshlrev_b32_e32 v72, 16, v64
	v_and_b32_e32 v64, 0xffff0000, v64
	v_mul_f32_e32 v64, v64, v64
	v_lshlrev_b32_e32 v73, 16, v65
	v_fmac_f32_e32 v64, v72, v72
	v_and_b32_e32 v65, 0xffff0000, v65
	v_fmac_f32_e32 v64, v73, v73
	v_lshlrev_b32_e32 v74, 16, v66
	v_fmac_f32_e32 v64, v65, v65
	v_and_b32_e32 v66, 0xffff0000, v66
	v_fmac_f32_e32 v64, v74, v74
	v_lshlrev_b32_e32 v75, 16, v67
	v_fmac_f32_e32 v64, v66, v66
	v_and_b32_e32 v67, 0xffff0000, v67
	v_fmac_f32_e32 v64, v75, v75
	v_lshlrev_b32_e32 v76, 16, v68
	v_fmac_f32_e32 v64, v67, v67
	v_and_b32_e32 v68, 0xffff0000, v68
	v_fmac_f32_e32 v64, v76, v76
	v_lshlrev_b32_e32 v77, 16, v69
	v_fmac_f32_e32 v64, v68, v68
	v_and_b32_e32 v69, 0xffff0000, v69
	v_fmac_f32_e32 v64, v77, v77
	v_lshlrev_b32_e32 v78, 16, v70
	v_fmac_f32_e32 v64, v69, v69
	v_and_b32_e32 v70, 0xffff0000, v70
	v_fmac_f32_e32 v64, v78, v78
	v_lshlrev_b32_e32 v79, 16, v71
	v_fmac_f32_e32 v64, v70, v70
	v_mfma_f32_32x32x16_bf16 v[48:63], v[140:143], v[96:99], v[48:63]
	v_and_b32_e32 v71, 0xffff0000, v71
	v_fmac_f32_e32 v64, v79, v79
	v_fmac_f32_e32 v64, v71, v71
	ds_bpermute_b32 v65, v185, v64
	s_and_saveexec_b64 s[6:7], vcc
	s_cbranch_execz .LBB0_567
	s_waitcnt lgkmcnt(0)
	v_add_f32_e32 v66, v64, v65
	v_add_u32_e32 v64, s21, v152
	v_lshl_add_u32 v152, v64, 5, s93
	v_lshl_add_u64 v[64:65], v[152:153], 2, s[18:19]
	global_store_dword v[64:65], v66, off
	s_branch .LBB0_567
